# baseline (speedup 1.0000x reference)
; __device__ __forceinline__ float exp2_(float x) { return __builtin_amdgcn_exp2f(x); }
; #define MFMA16(a, b, c) __builtin_amdgcn_mfma_f32_16x16x32_bf16((a), (b), (c), 0, 0, 0)
; template <int MODE, bool MASKED> ...
;   f32x4 s[2][2];
; #pragma unroll
;   for (int a = 0; a < 2; ++a)
; #pragma unroll
;     for (int mt = 0; mt < 2; ++mt) s[a][mt] = f32x4{0.f, 0.f, 0.f, 0.f};
; #pragma unroll
;   for (int a = 0; a < 2; ++a) {
;     const u16* kr = KL + (a * 16 + fr) * 136 + fq * 8;
; #pragma unroll
;     for (int kk = 0; kk < 4; ++kk) {
;       bf16x8 kf = *(const bf16x8*)(kr + kk * 32);
;       s[a][0] = MFMA16(kf, qf[0][kk], s[a][0]);
;       s[a][1] = MFMA16(kf, qf[1][kk], s[a][1]);
;     }
;   }
;   bf16x8 pf[2];
; #pragma unroll
;   for (int mt = 0; mt < 2; ++mt) {
;     const int d0 = dq[mt] - key0;
;     const float base = slope2 * (float)d0 + M2;
;     float pv[8];
;     float ps = 0.f;
; #pragma unroll
;     for (int a = 0; a < 2; ++a)
; #pragma unroll
;       for (int j = 0; j < 4; ++j) {
;         float x = (s[a][mt][j] - base) + slope2 * (float)(a * 16 + j);
;         float e = exp2_(x);
;         if (MASKED) {
;           int dist = d0 - (a * 16 + j);
;           bool v = (dist >= 0);
;           if (MODE == 1) v = v && rsel[mt];
;           if (MODE == 2) v = v && (dist < 512);
;           e = v ? e : 0.f;
;         }
;         pv[a * 4 + j] = e;
;         ps += e;
;       }
;     lrun[mt] += ps;
;     pf[mt] = as_bf16x8(pack8(pv));
;   }
; #pragma unroll
;   for (int dt = 0; dt < 8; ++dt) {
;     bf16x8 vf = *(const bf16x8*)(VL + (dt * 16 + fr) * 32 + fq * 8);
;     O[dt][0] = MFMA16(vf, pf[0], O[dt][0]);
;     O[dt][1] = MFMA16(vf, pf[1], O[dt][1]);
;   }
.LBB0_351:
	s_lshl_b32 s6, 1, s53
	s_waitcnt lgkmcnt(0)
	v_and_b32_e32 v112, s6, v172
	v_cmp_ne_u32_e32 vcc, 0, v112
	s_and_saveexec_b64 s[14:15], vcc
	s_cbranch_execz .LBB0_365
	v_lshrrev_b32_e32 v112, s53, v168
	s_and_b32 s8, s52, 1
	v_lshrrev_b32_e32 v113, s53, v159
	v_and_b32_e32 v112, 1, v112
	s_mul_i32 s9, s8, 0x4400
	s_lshl_b32 s8, s8, 14
	v_and_b32_e32 v113, 1, v113
	v_cmp_eq_u32_e32 vcc, 1, v112
	v_and_b32_e32 v112, s6, v175
	s_lshl_b32 s56, s53, 6
	s_add_i32 s57, s9, 0
	s_add_i32 s55, s8, 0
	v_cmp_eq_u32_e64 s[4:5], 1, v113
	v_cmp_eq_u32_e64 s[6:7], 0, v112
	s_add_i32 s57, s57, 0x13240
	s_add_i32 s55, s55, 0x1ba40
	v_cmp_le_i32_e64 s[8:9], s56, v202
	s_and_saveexec_b64 s[28:29], s[8:9]
	s_cbranch_execz .LBB0_358
	v_add3_u32 v112, s57, v144, v208
	ds_read_b128 v[140:143], v112
	ds_read_b128 v[136:139], v112 offset:64
	ds_read_b128 v[132:135], v112 offset:128
	ds_read_b128 v[128:131], v112 offset:192
	ds_read_b128 v[124:127], v112 offset:4352
	ds_read_b128 v[120:123], v112 offset:4416
	ds_read_b128 v[116:119], v112 offset:4480
	ds_read_b128 v[112:115], v112 offset:4544
	v_subrev_u32_e32 v178, s56, v176
	v_cvt_f32_i32_e32 v179, v178
	v_subrev_u32_e32 v180, s56, v177
	s_or_b32 s8, s56, 31
	v_cmp_le_i32_e64 s[8:9], s8, v201
	s_waitcnt vmcnt(0)
	v_fma_f32 v181, v205, v179, v173
	v_cvt_f32_i32_e32 v179, v180
	s_xor_b64 s[30:31], s[6:7], -1
	s_and_b64 s[8:9], s[30:31], s[8:9]
	s_and_saveexec_b64 s[30:31], s[8:9]
	s_xor_b64 s[8:9], exec, s[30:31]
	s_cbranch_execz .LBB0_355
	s_waitcnt lgkmcnt(7)
	v_mfma_f32_16x16x32_bf16 v[184:187], v[140:143], v[8:11], 0
	v_mfma_f32_16x16x32_bf16 v[140:143], v[140:143], v[24:27], 0
	s_waitcnt lgkmcnt(6)
	v_mfma_f32_16x16x32_bf16 v[184:187], v[136:139], v[0:3], v[184:187]
	v_mfma_f32_16x16x32_bf16 v[136:139], v[136:139], v[16:19], v[140:143]
	s_waitcnt lgkmcnt(5)
	v_mfma_f32_16x16x32_bf16 v[140:143], v[132:135], v[4:7], v[184:187]
	v_mfma_f32_16x16x32_bf16 v[132:135], v[132:135], v[20:23], v[136:139]
	s_waitcnt lgkmcnt(4)
	v_mfma_f32_16x16x32_bf16 v[136:139], v[128:131], v[12:15], v[140:143]
	v_mfma_f32_16x16x32_bf16 v[128:131], v[128:131], v[28:31], v[132:135]
	s_waitcnt lgkmcnt(3)
	v_mfma_f32_16x16x32_bf16 v[132:135], v[124:127], v[8:11], 0
	v_mfma_f32_16x16x32_bf16 v[124:127], v[124:127], v[24:27], 0
	s_waitcnt lgkmcnt(2)
	v_mfma_f32_16x16x32_bf16 v[132:135], v[120:123], v[0:3], v[132:135]
	v_mfma_f32_16x16x32_bf16 v[120:123], v[120:123], v[16:19], v[124:127]
	s_waitcnt lgkmcnt(1)
	v_mfma_f32_16x16x32_bf16 v[124:127], v[116:119], v[4:7], v[132:135]
	v_mfma_f32_16x16x32_bf16 v[116:119], v[116:119], v[20:23], v[120:123]
	s_waitcnt lgkmcnt(0)
	v_mfma_f32_16x16x32_bf16 v[120:123], v[112:115], v[12:15], v[124:127]
	v_mfma_f32_16x16x32_bf16 v[116:119], v[112:115], v[28:31], v[116:119]
	v_sub_f32_e32 v112, v136, v181
	v_add_f32_e32 v112, v212, v112
	s_nop 1
	v_exp_f32_e32 v125, v112
	v_sub_f32_e32 v112, v137, v181
	v_add_f32_e32 v112, v205, v112
	v_exp_f32_e32 v127, v112
	v_sub_f32_e32 v112, v138, v181
	v_add_f32_e32 v112, v213, v112
	v_exp_f32_e32 v133, v112
	v_sub_f32_e32 v112, v139, v181
	v_add_f32_e32 v112, v214, v112
	v_exp_f32_e32 v135, v112
	v_sub_f32_e32 v112, v120, v181
	v_add_f32_e32 v112, v215, v112
	v_exp_f32_e32 v137, v112
	v_sub_f32_e32 v112, v121, v181
	v_add_f32_e32 v112, v216, v112
	v_exp_f32_e32 v121, v112
	v_sub_f32_e32 v112, v122, v181
	v_fma_f32 v122, v205, v179, v173
	v_sub_f32_e32 v120, v128, v122
	v_add_f32_e32 v120, v212, v120
	v_exp_f32_e32 v124, v120
	v_sub_f32_e32 v120, v129, v122
	v_add_f32_e32 v120, v205, v120
	v_exp_f32_e32 v126, v120
	v_sub_f32_e32 v120, v130, v122
	v_sub_f32_e32 v116, v116, v122
	v_add_f32_e32 v120, v213, v120
	v_add_f32_e32 v116, v215, v116
	v_exp_f32_e32 v132, v120
	v_sub_f32_e32 v120, v131, v122
	v_exp_f32_e32 v136, v116
	v_sub_f32_e32 v116, v117, v122
	v_add_f32_e32 v120, v214, v120
	v_add_f32_e32 v116, v216, v116
	v_exp_f32_e32 v134, v120
	v_exp_f32_e32 v120, v116
	v_sub_f32_e32 v116, v118, v122
	v_add_f32_e32 v116, v217, v116
	v_add_f32_e32 v112, v217, v112
	v_pk_add_f32 v[128:129], v[124:125], 0 op_sel_hi:[1,0]
	v_exp_f32_e32 v138, v116
	v_sub_f32_e32 v116, v119, v122
	v_exp_f32_e32 v139, v112
	v_sub_f32_e32 v112, v123, v181
	v_pk_add_f32 v[128:129], v[126:127], v[128:129]
	v_add_f32_e32 v116, v218, v116
	v_add_f32_e32 v112, v218, v112
	v_exp_f32_e32 v122, v116
	v_pk_add_f32 v[116:117], v[132:133], v[128:129]
	v_exp_f32_e32 v123, v112
	v_pk_add_f32 v[116:117], v[134:135], v[116:117]
	v_cvt_pk_bf16_f32 v114, v137, v121
	v_pk_add_f32 v[116:117], v[116:117], v[136:137]
	v_cvt_pk_bf16_f32 v115, v139, v123
	v_pk_add_f32 v[116:117], v[120:121], v[116:117]
	v_cvt_pk_bf16_f32 v118, v136, v120
	v_pk_add_f32 v[116:117], v[138:139], v[116:117]
	v_cvt_pk_bf16_f32 v119, v138, v122
	v_pk_add_f32 v[116:117], v[122:123], v[116:117]
	v_cvt_pk_bf16_f32 v112, v125, v127
	v_pk_add_f32 v[166:167], v[166:167], v[116:117]
	v_cvt_pk_bf16_f32 v116, v124, v126
	v_add3_u32 v124, s55, v144, v219
	ds_read_b128 v[120:123], v124
	ds_read_b128 v[238:241], v124 offset:1024
	ds_read_b128 v[242:245], v124 offset:2048
	ds_read_b128 v[250:253], v124 offset:3072
	v_cvt_pk_bf16_f32 v113, v133, v135
	v_cvt_pk_bf16_f32 v117, v132, v134
	s_waitcnt lgkmcnt(3)
	v_mfma_f32_16x16x32_bf16 v[108:111], v[120:123], v[112:115], v[108:111]
	v_mfma_f32_16x16x32_bf16 v[76:79], v[120:123], v[116:119], v[76:79]
	ds_read_b128 v[120:123], v124 offset:4096
	s_waitcnt lgkmcnt(3)
	v_mfma_f32_16x16x32_bf16 v[104:107], v[238:241], v[112:115], v[104:107]
	v_mfma_f32_16x16x32_bf16 v[72:75], v[238:241], v[116:119], v[72:75]
	ds_read_b128 v[238:241], v124 offset:5120
	s_waitcnt lgkmcnt(3)
	v_mfma_f32_16x16x32_bf16 v[100:103], v[242:245], v[112:115], v[100:103]
	v_mfma_f32_16x16x32_bf16 v[68:71], v[242:245], v[116:119], v[68:71]
	ds_read_b128 v[242:245], v124 offset:6144
	s_waitcnt lgkmcnt(3)
	v_mfma_f32_16x16x32_bf16 v[96:99], v[250:253], v[112:115], v[96:99]
	v_mfma_f32_16x16x32_bf16 v[64:67], v[250:253], v[116:119], v[64:67]
	ds_read_b128 v[250:253], v124 offset:7168
	s_waitcnt lgkmcnt(3)
	v_mfma_f32_16x16x32_bf16 v[92:95], v[120:123], v[112:115], v[92:95]
	v_mfma_f32_16x16x32_bf16 v[60:63], v[120:123], v[116:119], v[60:63]
	s_waitcnt lgkmcnt(2)
	v_mfma_f32_16x16x32_bf16 v[88:91], v[238:241], v[112:115], v[88:91]
	v_mfma_f32_16x16x32_bf16 v[56:59], v[238:241], v[116:119], v[56:59]
	s_waitcnt lgkmcnt(1)
	v_mfma_f32_16x16x32_bf16 v[84:87], v[242:245], v[112:115], v[84:87]
	v_mfma_f32_16x16x32_bf16 v[52:55], v[242:245], v[116:119], v[52:55]
	s_waitcnt lgkmcnt(0)
	v_mfma_f32_16x16x32_bf16 v[80:83], v[250:253], v[112:115], v[80:83]
	v_mfma_f32_16x16x32_bf16 v[48:51], v[250:253], v[116:119], v[48:51]
; __device__ __forceinline__ float exp2_(float x) { return __builtin_amdgcn_exp2f(x); }
; #define MFMA16(a, b, c) __builtin_amdgcn_mfma_f32_16x16x32_bf16((a), (b), (c), 0, 0, 0)
; template <int MODE, bool MASKED> ...
;   f32x4 s[2][2];
; #pragma unroll
;   for (int a = 0; a < 2; ++a)
; #pragma unroll
;     for (int mt = 0; mt < 2; ++mt) s[a][mt] = f32x4{0.f, 0.f, 0.f, 0.f};
; #pragma unroll
;   for (int a = 0; a < 2; ++a) {
;     const u16* kr = KL + (a * 16 + fr) * 136 + fq * 8;
; #pragma unroll
;     for (int kk = 0; kk < 4; ++kk) {
;       bf16x8 kf = *(const bf16x8*)(kr + kk * 32);
;       s[a][0] = MFMA16(kf, qf[0][kk], s[a][0]);
;       s[a][1] = MFMA16(kf, qf[1][kk], s[a][1]);
;     }
;   }
;   bf16x8 pf[2];
; #pragma unroll
;   for (int mt = 0; mt < 2; ++mt) {
;     const int d0 = dq[mt] - key0;
;     const float base = slope2 * (float)d0 + M2;
;     float pv[8];
;     float ps = 0.f;
; #pragma unroll
;     for (int a = 0; a < 2; ++a)
; #pragma unroll
;       for (int j = 0; j < 4; ++j) {
;         float x = (s[a][mt][j] - base) + slope2 * (float)(a * 16 + j);
;         float e = exp2_(x);
;         if (MASKED) {
;           int dist = d0 - (a * 16 + j);
;           bool v = (dist >= 0);
;           if (MODE == 1) v = v && rsel[mt];
;           if (MODE == 2) v = v && (dist < 512);
;           e = v ? e : 0.f;
;         }
;         pv[a * 4 + j] = e;
;         ps += e;
;       }
;     lrun[mt] += ps;
;     pf[mt] = as_bf16x8(pack8(pv));
;   }
; #pragma unroll
;   for (int dt = 0; dt < 8; ++dt) {
;     bf16x8 vf = *(const bf16x8*)(VL + (dt * 16 + fr) * 32 + fq * 8);
;     O[dt][0] = MFMA16(vf, pf[0], O[dt][0]);
;     O[dt][1] = MFMA16(vf, pf[1], O[dt][1]);
;   }
.LBB0_355:
	s_andn2_saveexec_b64 s[30:31], s[8:9]
	s_cbranch_execz .LBB0_357
	s_waitcnt lgkmcnt(7)
	v_mfma_f32_16x16x32_bf16 v[184:187], v[140:143], v[8:11], 0
	v_cmp_lt_i32_e64 s[8:9], 1, v178
	s_and_b64 s[8:9], s[8:9], s[4:5]
	v_mfma_f32_16x16x32_bf16 v[140:143], v[140:143], v[24:27], 0
	s_waitcnt lgkmcnt(6)
	v_mfma_f32_16x16x32_bf16 v[184:187], v[136:139], v[0:3], v[184:187]
	v_mfma_f32_16x16x32_bf16 v[136:139], v[136:139], v[16:19], v[140:143]
	s_waitcnt lgkmcnt(5)
	v_mfma_f32_16x16x32_bf16 v[140:143], v[132:135], v[4:7], v[184:187]
	v_mfma_f32_16x16x32_bf16 v[132:135], v[132:135], v[20:23], v[136:139]
	s_waitcnt lgkmcnt(4)
	v_mfma_f32_16x16x32_bf16 v[136:139], v[128:131], v[12:15], v[140:143]
	v_mfma_f32_16x16x32_bf16 v[128:131], v[128:131], v[28:31], v[132:135]
	s_waitcnt lgkmcnt(3)
	v_mfma_f32_16x16x32_bf16 v[132:135], v[124:127], v[8:11], 0
	v_mfma_f32_16x16x32_bf16 v[124:127], v[124:127], v[24:27], 0
	s_waitcnt lgkmcnt(2)
	v_mfma_f32_16x16x32_bf16 v[132:135], v[120:123], v[0:3], v[132:135]
	v_mfma_f32_16x16x32_bf16 v[120:123], v[120:123], v[16:19], v[124:127]
	s_waitcnt lgkmcnt(1)
	v_mfma_f32_16x16x32_bf16 v[124:127], v[116:119], v[4:7], v[132:135]
	v_mfma_f32_16x16x32_bf16 v[116:119], v[116:119], v[20:23], v[120:123]
	s_waitcnt lgkmcnt(0)
	v_mfma_f32_16x16x32_bf16 v[120:123], v[112:115], v[12:15], v[124:127]
	v_mfma_f32_16x16x32_bf16 v[112:115], v[112:115], v[28:31], v[116:119]
	s_nop 4
	v_sub_f32_e32 v117, v137, v181
	v_add_f32_e32 v117, v205, v117
	v_exp_f32_e32 v124, v117
	v_sub_f32_e32 v117, v138, v181
	v_add_f32_e32 v117, v213, v117
	v_exp_f32_e32 v117, v117
	v_sub_f32_e32 v116, v136, v181
	v_add_f32_e32 v116, v212, v116
	v_exp_f32_e32 v116, v116
	v_cndmask_b32_e64 v119, 0, v117, s[8:9]
	v_sub_f32_e32 v117, v139, v181
	v_add_f32_e32 v117, v214, v117
	v_exp_f32_e32 v125, v117
	v_sub_f32_e32 v117, v120, v181
	v_add_f32_e32 v117, v215, v117
	v_exp_f32_e32 v126, v117
	v_sub_f32_e32 v117, v121, v181
	v_add_f32_e32 v117, v216, v117
	v_exp_f32_e32 v127, v117
	v_sub_f32_e32 v117, v122, v181
	v_add_f32_e32 v117, v217, v117
	v_exp_f32_e32 v132, v117
	v_sub_f32_e32 v117, v123, v181
	v_add_f32_e32 v117, v218, v117
	v_exp_f32_e32 v133, v117
	v_fma_f32 v117, v205, v179, v173
	v_sub_f32_e32 v118, v128, v117
	v_add_f32_e32 v118, v212, v118
	v_exp_f32_e32 v120, v118
	v_sub_f32_e32 v118, v129, v117
	v_add_f32_e32 v118, v205, v118
	v_exp_f32_e32 v122, v118
	v_sub_f32_e32 v118, v130, v117
	v_add_f32_e32 v118, v213, v118
	v_exp_f32_e32 v118, v118
	v_sub_f32_e32 v112, v112, v117
	v_add_f32_e32 v112, v215, v112
	v_cmp_lt_i32_e64 s[8:9], 1, v180
	v_exp_f32_e32 v129, v112
	v_sub_f32_e32 v112, v113, v117
	s_and_b64 s[8:9], s[8:9], vcc
	v_add_f32_e32 v112, v216, v112
	v_cndmask_b32_e64 v118, 0, v118, s[8:9]
	v_exp_f32_e32 v130, v112
	v_sub_f32_e32 v112, v114, v117
	v_cmp_lt_i32_e64 s[8:9], -1, v178
	v_add_f32_e32 v112, v217, v112
	s_and_b64 s[8:9], s[8:9], s[4:5]
	v_sub_f32_e32 v121, v131, v117
	v_exp_f32_e32 v131, v112
	v_sub_f32_e32 v112, v115, v117
	v_cndmask_b32_e64 v117, 0, v116, s[8:9]
	v_cmp_lt_i32_e64 s[8:9], -1, v180
	s_and_b64 s[8:9], s[8:9], vcc
	v_add_f32_e32 v121, v214, v121
	v_cndmask_b32_e64 v116, 0, v120, s[8:9]
	v_cmp_lt_i32_e64 s[8:9], 0, v178
	s_and_b64 s[8:9], s[8:9], s[4:5]
	v_exp_f32_e32 v128, v121
	v_cndmask_b32_e64 v121, 0, v124, s[8:9]
	v_cmp_lt_i32_e64 s[8:9], 0, v180
	s_and_b64 s[8:9], s[8:9], vcc
	v_add_f32_e32 v112, v218, v112
	v_cndmask_b32_e64 v120, 0, v122, s[8:9]
	v_cmp_lt_i32_e64 s[8:9], 2, v178
	s_and_b64 s[8:9], s[8:9], s[4:5]
	v_exp_f32_e32 v134, v112
	v_cndmask_b32_e64 v123, 0, v125, s[8:9]
	v_cmp_lt_i32_e64 s[8:9], 2, v180
	s_and_b64 s[8:9], s[8:9], vcc
	v_pk_add_f32 v[112:113], v[116:117], 0 op_sel_hi:[1,0]
	v_cndmask_b32_e64 v122, 0, v128, s[8:9]
	v_cmp_lt_i32_e64 s[8:9], 15, v178
	s_and_b64 s[8:9], s[8:9], s[4:5]
	v_pk_add_f32 v[114:115], v[120:121], v[112:113]
	v_cndmask_b32_e64 v125, 0, v126, s[8:9]
	v_cmp_lt_i32_e64 s[8:9], 15, v180
	s_and_b64 s[8:9], s[8:9], vcc
	v_pk_add_f32 v[114:115], v[118:119], v[114:115]
	v_cndmask_b32_e64 v124, 0, v129, s[8:9]
	v_cmp_lt_i32_e64 s[8:9], 16, v178
	s_and_b64 s[8:9], s[8:9], s[4:5]
	v_pk_add_f32 v[114:115], v[122:123], v[114:115]
	v_cndmask_b32_e64 v127, 0, v127, s[8:9]
	v_cmp_lt_i32_e64 s[8:9], 16, v180
	s_and_b64 s[8:9], s[8:9], vcc
	v_cvt_pk_bf16_f32 v112, v117, v121
	v_cndmask_b32_e64 v126, 0, v130, s[8:9]
	v_cmp_lt_i32_e64 s[8:9], 17, v178
	v_pk_add_f32 v[114:115], v[114:115], v[124:125]
	v_cvt_pk_bf16_f32 v117, v118, v122
	v_cvt_pk_bf16_f32 v118, v124, v126
	v_add3_u32 v124, s55, v144, v219
	s_and_b64 s[8:9], s[8:9], s[4:5]
	v_cvt_pk_bf16_f32 v113, v119, v123
	v_cvt_pk_bf16_f32 v116, v116, v120
	ds_read_b128 v[120:123], v124
	ds_read_b128 v[238:241], v124 offset:1024
	ds_read_b128 v[242:245], v124 offset:2048
	ds_read_b128 v[250:253], v124 offset:3072
	v_cndmask_b32_e64 v129, 0, v132, s[8:9]
	v_cmp_lt_i32_e64 s[8:9], 17, v180
	s_and_b64 s[8:9], s[8:9], vcc
	v_pk_add_f32 v[114:115], v[126:127], v[114:115]
	v_cndmask_b32_e64 v128, 0, v131, s[8:9]
	v_cmp_lt_i32_e64 s[8:9], 18, v178
	s_and_b64 s[8:9], s[8:9], s[4:5]
	v_pk_add_f32 v[114:115], v[128:129], v[114:115]
	v_cndmask_b32_e64 v131, 0, v133, s[8:9]
	v_cmp_lt_i32_e64 s[8:9], 18, v180
	s_and_b64 s[8:9], s[8:9], vcc
	s_nop 0
	v_cndmask_b32_e64 v130, 0, v134, s[8:9]
	v_pk_add_f32 v[132:133], v[130:131], v[114:115]
	v_cvt_pk_bf16_f32 v114, v125, v127
	v_cvt_pk_bf16_f32 v115, v129, v131
	v_cvt_pk_bf16_f32 v119, v128, v130
	v_pk_add_f32 v[166:167], v[166:167], v[132:133]
	s_waitcnt lgkmcnt(3)
	v_mfma_f32_16x16x32_bf16 v[108:111], v[120:123], v[112:115], v[108:111]
	v_mfma_f32_16x16x32_bf16 v[76:79], v[120:123], v[116:119], v[76:79]
	ds_read_b128 v[120:123], v124 offset:4096
	s_waitcnt lgkmcnt(3)
	v_mfma_f32_16x16x32_bf16 v[104:107], v[238:241], v[112:115], v[104:107]
	v_mfma_f32_16x16x32_bf16 v[72:75], v[238:241], v[116:119], v[72:75]
	ds_read_b128 v[238:241], v124 offset:5120
	s_waitcnt lgkmcnt(3)
	v_mfma_f32_16x16x32_bf16 v[100:103], v[242:245], v[112:115], v[100:103]
	v_mfma_f32_16x16x32_bf16 v[68:71], v[242:245], v[116:119], v[68:71]
	ds_read_b128 v[242:245], v124 offset:6144
	s_waitcnt lgkmcnt(3)
	v_mfma_f32_16x16x32_bf16 v[96:99], v[250:253], v[112:115], v[96:99]
	v_mfma_f32_16x16x32_bf16 v[64:67], v[250:253], v[116:119], v[64:67]
	ds_read_b128 v[250:253], v124 offset:7168
	s_waitcnt lgkmcnt(3)
	v_mfma_f32_16x16x32_bf16 v[92:95], v[120:123], v[112:115], v[92:95]
	v_mfma_f32_16x16x32_bf16 v[60:63], v[120:123], v[116:119], v[60:63]
	s_waitcnt lgkmcnt(2)
	v_mfma_f32_16x16x32_bf16 v[88:91], v[238:241], v[112:115], v[88:91]
	v_mfma_f32_16x16x32_bf16 v[56:59], v[238:241], v[116:119], v[56:59]
	s_waitcnt lgkmcnt(1)
	v_mfma_f32_16x16x32_bf16 v[84:87], v[242:245], v[112:115], v[84:87]
	v_mfma_f32_16x16x32_bf16 v[52:55], v[242:245], v[116:119], v[52:55]
	s_waitcnt lgkmcnt(0)
	v_mfma_f32_16x16x32_bf16 v[80:83], v[250:253], v[112:115], v[80:83]
	v_mfma_f32_16x16x32_bf16 v[48:51], v[250:253], v[116:119], v[48:51]

; __device__ __forceinline__ float exp2_(float x) { return __builtin_amdgcn_exp2f(x); }
; #define MFMA16(a, b, c) __builtin_amdgcn_mfma_f32_16x16x32_bf16((a), (b), (c), 0, 0, 0)
; template <int MODE, bool MASKED> ...
;   f32x4 s[2][2];
; #pragma unroll
;   for (int a = 0; a < 2; ++a)
; #pragma unroll
;     for (int mt = 0; mt < 2; ++mt) s[a][mt] = f32x4{0.f, 0.f, 0.f, 0.f};
; #pragma unroll
;   for (int a = 0; a < 2; ++a) {
;     const u16* kr = KL + (a * 16 + fr) * 136 + fq * 8;
; #pragma unroll
;     for (int kk = 0; kk < 4; ++kk) {
;       bf16x8 kf = *(const bf16x8*)(kr + kk * 32);
;       s[a][0] = MFMA16(kf, qf[0][kk], s[a][0]);
;       s[a][1] = MFMA16(kf, qf[1][kk], s[a][1]);
;     }
;   }
;   bf16x8 pf[2];
; #pragma unroll
;   for (int mt = 0; mt < 2; ++mt) {
;     const int d0 = dq[mt] - key0;
;     const float base = slope2 * (float)d0 + M2;
;     float pv[8];
;     float ps = 0.f;
; #pragma unroll
;     for (int a = 0; a < 2; ++a)
; #pragma unroll
;       for (int j = 0; j < 4; ++j) {
;         float x = (s[a][mt][j] - base) + slope2 * (float)(a * 16 + j);
;         float e = exp2_(x);
;         if (MASKED) {
;           int dist = d0 - (a * 16 + j);
;           bool v = (dist >= 0);
;           if (MODE == 1) v = v && rsel[mt];
;           if (MODE == 2) v = v && (dist < 512);
;           e = v ? e : 0.f;
;         }
;         pv[a * 4 + j] = e;
;         ps += e;
;       }
;     lrun[mt] += ps;
;     pf[mt] = as_bf16x8(pack8(pv));
;   }
; #pragma unroll
;   for (int dt = 0; dt < 8; ++dt) {
;     bf16x8 vf = *(const bf16x8*)(VL + (dt * 16 + fr) * 32 + fq * 8);
;     O[dt][0] = MFMA16(vf, pf[0], O[dt][0]);
;     O[dt][1] = MFMA16(vf, pf[1], O[dt][1]);
;   }
.LBB0_361:
	s_andn2_saveexec_b64 s[8:9], s[6:7]
	s_cbranch_execz .LBB0_363
	s_waitcnt lgkmcnt(7)
	v_mfma_f32_16x16x32_bf16 v[184:187], v[140:143], v[8:11], 0
	v_cmp_lt_i32_e64 s[6:7], -1, v179
	s_and_b64 s[6:7], s[6:7], s[4:5]
	v_mfma_f32_16x16x32_bf16 v[140:143], v[140:143], v[24:27], 0
	s_waitcnt lgkmcnt(6)
	v_mfma_f32_16x16x32_bf16 v[184:187], v[136:139], v[0:3], v[184:187]
	v_mfma_f32_16x16x32_bf16 v[136:139], v[136:139], v[16:19], v[140:143]
	s_waitcnt lgkmcnt(5)
	v_mfma_f32_16x16x32_bf16 v[140:143], v[132:135], v[4:7], v[184:187]
	v_mfma_f32_16x16x32_bf16 v[132:135], v[132:135], v[20:23], v[136:139]
	s_waitcnt lgkmcnt(4)
	v_mfma_f32_16x16x32_bf16 v[136:139], v[128:131], v[12:15], v[140:143]
	v_mfma_f32_16x16x32_bf16 v[128:131], v[128:131], v[28:31], v[132:135]
	s_waitcnt lgkmcnt(3)
	v_mfma_f32_16x16x32_bf16 v[132:135], v[124:127], v[8:11], 0
	v_mfma_f32_16x16x32_bf16 v[124:127], v[124:127], v[24:27], 0
	s_waitcnt lgkmcnt(2)
	v_mfma_f32_16x16x32_bf16 v[132:135], v[120:123], v[0:3], v[132:135]
	v_mfma_f32_16x16x32_bf16 v[120:123], v[120:123], v[16:19], v[124:127]
	s_waitcnt lgkmcnt(1)
	v_mfma_f32_16x16x32_bf16 v[124:127], v[116:119], v[4:7], v[132:135]
	v_mfma_f32_16x16x32_bf16 v[116:119], v[116:119], v[20:23], v[120:123]
	s_waitcnt lgkmcnt(0)
	v_mfma_f32_16x16x32_bf16 v[120:123], v[112:115], v[12:15], v[124:127]
	v_mfma_f32_16x16x32_bf16 v[112:115], v[112:115], v[28:31], v[116:119]
	s_nop 4
	v_sub_f32_e32 v116, v136, v181
	v_add_f32_e32 v116, v212, v116
	v_exp_f32_e32 v116, v116
	v_fma_f32 v119, v205, v178, v173
	v_sub_f32_e32 v112, v112, v119
	v_sub_f32_e32 v113, v113, v119
	v_cndmask_b32_e64 v117, 0, v116, s[6:7]
	v_sub_f32_e32 v116, v137, v181
	v_add_f32_e32 v116, v205, v116
	v_exp_f32_e32 v118, v116
	v_sub_f32_e32 v116, v138, v181
	v_add_f32_e32 v116, v213, v116
	v_exp_f32_e32 v124, v116
	v_sub_f32_e32 v116, v139, v181
	v_add_f32_e32 v116, v214, v116
	v_exp_f32_e32 v125, v116
	v_sub_f32_e32 v116, v120, v181
	v_add_f32_e32 v116, v215, v116
	v_exp_f32_e32 v126, v116
	v_sub_f32_e32 v116, v121, v181
	v_add_f32_e32 v116, v216, v116
	v_exp_f32_e32 v127, v116
	v_sub_f32_e32 v116, v122, v181
	v_add_f32_e32 v116, v217, v116
	v_exp_f32_e32 v132, v116
	v_sub_f32_e32 v116, v123, v181
	v_add_f32_e32 v116, v218, v116
	v_exp_f32_e32 v133, v116
	v_sub_f32_e32 v116, v128, v119
	v_add_f32_e32 v116, v212, v116
	v_exp_f32_e32 v116, v116
	v_cmp_lt_i32_e64 s[6:7], -1, v180
	v_sub_f32_e32 v120, v129, v119
	s_and_b64 s[6:7], s[6:7], vcc
	v_add_f32_e32 v120, v205, v120
	v_cndmask_b32_e64 v116, 0, v116, s[6:7]
	v_exp_f32_e32 v120, v120
	v_sub_f32_e32 v121, v130, v119
	v_cmp_lt_i32_e64 s[6:7], 0, v179
	v_add_f32_e32 v121, v213, v121
	s_and_b64 s[6:7], s[6:7], s[4:5]
	v_exp_f32_e32 v122, v121
	v_sub_f32_e32 v121, v131, v119
	v_sub_f32_e32 v114, v114, v119
	v_sub_f32_e32 v115, v115, v119
	v_cndmask_b32_e64 v119, 0, v118, s[6:7]
	v_cmp_lt_i32_e64 s[6:7], 0, v180
	s_and_b64 s[6:7], s[6:7], vcc
	v_add_f32_e32 v121, v214, v121
	v_cndmask_b32_e64 v118, 0, v120, s[6:7]
	v_cmp_lt_i32_e64 s[6:7], 1, v179
	s_and_b64 s[6:7], s[6:7], s[4:5]
	v_exp_f32_e32 v128, v121
	v_cndmask_b32_e64 v121, 0, v124, s[6:7]
	v_cmp_lt_i32_e64 s[6:7], 1, v180
	s_and_b64 s[6:7], s[6:7], vcc
	v_add_f32_e32 v112, v215, v112
	v_cndmask_b32_e64 v120, 0, v122, s[6:7]
	v_cmp_lt_i32_e64 s[6:7], 2, v179
	s_and_b64 s[6:7], s[6:7], s[4:5]
	v_exp_f32_e32 v112, v112
	v_cndmask_b32_e64 v123, 0, v125, s[6:7]
	v_cmp_lt_i32_e64 s[6:7], 2, v180
	s_and_b64 s[6:7], s[6:7], vcc
	v_add_f32_e32 v113, v216, v113
	v_cndmask_b32_e64 v122, 0, v128, s[6:7]
	v_cmp_lt_i32_e64 s[6:7], 15, v179
	s_and_b64 s[6:7], s[6:7], s[4:5]
	v_exp_f32_e32 v113, v113
	v_cndmask_b32_e64 v125, 0, v126, s[6:7]
	v_cmp_lt_i32_e64 s[6:7], 15, v180
	s_and_b64 s[6:7], s[6:7], vcc
	v_add_f32_e32 v114, v217, v114
	v_cndmask_b32_e64 v124, 0, v112, s[6:7]
	v_cmp_lt_i32_e64 s[6:7], 16, v179
	s_and_b64 s[6:7], s[6:7], s[4:5]
	v_exp_f32_e32 v114, v114
	v_cndmask_b32_e64 v127, 0, v127, s[6:7]
	v_cmp_lt_i32_e64 s[6:7], 16, v180
	s_and_b64 s[6:7], s[6:7], vcc
	v_add_f32_e32 v115, v218, v115
	v_cndmask_b32_e64 v126, 0, v113, s[6:7]
	v_cmp_lt_i32_e64 s[6:7], 17, v179
	s_and_b64 s[6:7], s[6:7], s[4:5]
	v_pk_add_f32 v[112:113], v[116:117], 0 op_sel_hi:[1,0]
	v_cndmask_b32_e64 v129, 0, v132, s[6:7]
	v_cmp_lt_i32_e64 s[6:7], 17, v180
	s_and_b64 s[6:7], s[6:7], vcc
	v_pk_add_f32 v[112:113], v[118:119], v[112:113]
	v_exp_f32_e32 v115, v115
	v_cndmask_b32_e64 v128, 0, v114, s[6:7]
	v_cmp_lt_i32_e64 s[6:7], 18, v179
	v_pk_add_f32 v[112:113], v[120:121], v[112:113]
	s_and_b64 s[4:5], s[6:7], s[4:5]
	v_pk_add_f32 v[112:113], v[122:123], v[112:113]
	v_cndmask_b32_e64 v131, 0, v133, s[4:5]
	v_cmp_lt_i32_e64 s[4:5], 18, v180
	v_pk_add_f32 v[112:113], v[112:113], v[124:125]
	s_and_b64 vcc, s[4:5], vcc
	v_pk_add_f32 v[112:113], v[126:127], v[112:113]
	v_cndmask_b32_e32 v130, 0, v115, vcc
	v_pk_add_f32 v[112:113], v[128:129], v[112:113]
	v_cvt_pk_bf16_f32 v116, v116, v118
	v_cvt_pk_bf16_f32 v118, v124, v126
	v_add3_u32 v124, s55, v144, v219
	v_pk_add_f32 v[132:133], v[130:131], v[112:113]
	v_cvt_pk_bf16_f32 v112, v117, v119
	v_cvt_pk_bf16_f32 v113, v121, v123
	v_cvt_pk_bf16_f32 v117, v120, v122
	ds_read_b128 v[120:123], v124 offset:8192
	ds_read_b128 v[238:241], v124 offset:9216
	ds_read_b128 v[242:245], v124 offset:10240
	ds_read_b128 v[250:253], v124 offset:11264
	v_cvt_pk_bf16_f32 v114, v125, v127
	v_cvt_pk_bf16_f32 v115, v129, v131
	v_cvt_pk_bf16_f32 v119, v128, v130
	v_pk_add_f32 v[166:167], v[166:167], v[132:133]
	s_waitcnt lgkmcnt(3)
	v_mfma_f32_16x16x32_bf16 v[108:111], v[120:123], v[112:115], v[108:111]
	v_mfma_f32_16x16x32_bf16 v[76:79], v[120:123], v[116:119], v[76:79]
	ds_read_b128 v[120:123], v124 offset:12288
	s_waitcnt lgkmcnt(3)
	v_mfma_f32_16x16x32_bf16 v[104:107], v[238:241], v[112:115], v[104:107]
	v_mfma_f32_16x16x32_bf16 v[72:75], v[238:241], v[116:119], v[72:75]
	ds_read_b128 v[238:241], v124 offset:13312
	s_waitcnt lgkmcnt(3)
	v_mfma_f32_16x16x32_bf16 v[100:103], v[242:245], v[112:115], v[100:103]
	v_mfma_f32_16x16x32_bf16 v[68:71], v[242:245], v[116:119], v[68:71]
	ds_read_b128 v[242:245], v124 offset:14336
	s_waitcnt lgkmcnt(3)
	v_mfma_f32_16x16x32_bf16 v[96:99], v[250:253], v[112:115], v[96:99]
	v_mfma_f32_16x16x32_bf16 v[64:67], v[250:253], v[116:119], v[64:67]
	ds_read_b128 v[250:253], v124 offset:15360
	s_waitcnt lgkmcnt(3)
	v_mfma_f32_16x16x32_bf16 v[92:95], v[120:123], v[112:115], v[92:95]
	v_mfma_f32_16x16x32_bf16 v[60:63], v[120:123], v[116:119], v[60:63]
	s_waitcnt lgkmcnt(2)
	v_mfma_f32_16x16x32_bf16 v[88:91], v[238:241], v[112:115], v[88:91]
	v_mfma_f32_16x16x32_bf16 v[56:59], v[238:241], v[116:119], v[56:59]
	s_waitcnt lgkmcnt(1)
	v_mfma_f32_16x16x32_bf16 v[84:87], v[242:245], v[112:115], v[84:87]
	v_mfma_f32_16x16x32_bf16 v[52:55], v[242:245], v[116:119], v[52:55]
	s_waitcnt lgkmcnt(0)
	v_mfma_f32_16x16x32_bf16 v[80:83], v[250:253], v[112:115], v[80:83]
	v_mfma_f32_16x16x32_bf16 v[48:51], v[250:253], v[116:119], v[48:51]
